# out-proj epilogue gate slots in LDS re-laid out at 16-byte lane stride (conflict-free ds_read_b128)
# baseline (speedup 1.0000x reference)
; #define MFMA32(a, b, c) __builtin_amdgcn_mfma_f32_32x32x16_bf16((a), (b), (c), 0, 0, 0)
; template <int EPI>
; DI void gemm_phase(const Params& p, char* lds, const bfu* __restrict__ A, const bfu* __restrict__ BT, int ntn, int l, const float* xin) {
;     ...
;       for (int s = 0; s < 4; ++s) {
;         if (s < 3) {
;           const unsigned co = (unsigned)((((s + 1) * 2 + h) ^ swz) << 4);
;           af[(s + 1) & 1][0] = *(const bf16x8*)(pa + co); af[(s + 1) & 1][1] = *(const bf16x8*)(pa + 4096 + co);
; #pragma unroll
;           for (int j = 0; j < 4; ++j) bfr[(s + 1) & 1][j] = *(const bf16x8*)(pb + j * 4096 + co);
;         }
;         SBAR();
; #pragma unroll
;         for (int i = 0; i < 2; ++i)
; #pragma unroll
;           for (int j = 0; j < 4; ++j) {
;             acc[i][j] = MFMA32(bfr[s & 1][j], af[s & 1][i], acc[i][j]);
;             if (s < 2 && (j & 1) && dnext) DMA_PIECE(dA, dB, dk, dso, s * 4 + i * 2 + (j >> 1));
;           }
;         SBAR();
;     ...
;       char* stg = lds + 65536 + wave * 8704;
;       const float* gate = (const float*)(p.ws + WS_MOD) + l * 6144 + (m0 >> 14) * 3072 + 2048;
;       float4 xn[8];
;     ...
;       LOADX(0);
; #pragma unroll
;       for (int ps = 0; ps < 4; ++ps) {
;         const int i = ps >> 1, jp = ps & 1;
;         float4 xc[8];
; #pragma unroll
;         for (int it = 0; it < 8; ++it) xc[it] = xn[it];
;         if (ps + 1 < 4) LOADX(ps + 1);
;         if (ps) WSYNC();
; #pragma unroll
;         for (int j2 = 0; j2 < 2; ++j2)
; #pragma unroll
;           for (int g = 0; g < 4; ++g) {
;             const f32x16& a = acc[i][2 * jp + j2];
;             float4 o; o.x = a[4 * g]; o.y = a[4 * g + 1]; o.z = a[4 * g + 2]; o.w = a[4 * g + 3];
;             *(float4*)(stg + r * 272 + (j2 * 32 + 8 * g + 4 * h) * 4) = o;
;           }
;         WSYNC();
; #pragma unroll
;         for (int it = 0; it < 8; ++it) {
;           const int id = it * 64 + lane, row = id >> 4, c = id & 15;
;           const float4 y = *(const float4*)(stg + row * 272 + c * 16);
;           const int m = m0 + wm * 64 + i * 32 + row, n = n0 + wn * 128 + jp * 64 + c * 4;
;           const float4 xv = xc[it];
;           const float4 gv = *(const float4*)(gate + n);
;           float4 o; o.x = xv.x + gv.x * y.x; o.y = xv.y + gv.y * y.y; o.z = xv.z + gv.z * y.z; o.w = xv.w + gv.w * y.w;
;           *(float4*)(p.out + (size_t)m * 1024 + n) = o;
.LBB0_801:
	v_add_u32_e32 v132, v209, v200
	v_add_u32_e32 v148, v210, v200
	ds_read_b128 v[128:131], v132
	ds_read_b128 v[132:135], v132 offset:4096
	ds_read_b128 v[136:139], v148 offset:32768
	ds_read_b128 v[140:143], v148 offset:36864
	ds_read_b128 v[144:147], v148 offset:40960
	ds_read_b128 v[148:151], v148 offset:45056
	s_waitcnt lgkmcnt(9)
	v_mfma_f32_32x32x16_bf16 v[112:127], v[172:175], v[164:167], v[112:127]
	s_waitcnt lgkmcnt(8)
	v_mfma_f32_32x32x16_bf16 v[96:111], v[168:171], v[164:167], v[96:111]
	s_waitcnt lgkmcnt(7)
	v_mfma_f32_32x32x16_bf16 v[80:95], v[160:163], v[164:167], v[80:95]
	s_waitcnt lgkmcnt(6)
	v_mfma_f32_32x32x16_bf16 v[64:79], v[156:159], v[164:167], v[64:79]
	v_mfma_f32_32x32x16_bf16 v[48:63], v[172:175], v[152:155], v[48:63]
	v_mfma_f32_32x32x16_bf16 v[32:47], v[168:171], v[152:155], v[32:47]
	v_mfma_f32_32x32x16_bf16 v[16:31], v[160:163], v[152:155], v[16:31]
	v_mfma_f32_32x32x16_bf16 v[0:15], v[156:159], v[152:155], v[0:15]
	s_waitcnt lgkmcnt(3)
	v_mfma_f32_32x32x16_bf16 v[112:127], v[136:139], v[128:131], v[112:127]
	s_waitcnt lgkmcnt(2)
	v_mfma_f32_32x32x16_bf16 v[96:111], v[140:143], v[128:131], v[96:111]
	s_waitcnt lgkmcnt(1)
	v_mfma_f32_32x32x16_bf16 v[80:95], v[144:147], v[128:131], v[80:95]
	s_waitcnt lgkmcnt(0)
	v_mfma_f32_32x32x16_bf16 v[64:79], v[148:151], v[128:131], v[64:79]
	v_mfma_f32_32x32x16_bf16 v[48:63], v[136:139], v[132:135], v[48:63]
	v_mfma_f32_32x32x16_bf16 v[32:47], v[140:143], v[132:135], v[32:47]
	v_mfma_f32_32x32x16_bf16 v[16:31], v[144:147], v[132:135], v[16:31]
	v_mfma_f32_32x32x16_bf16 v[0:15], v[148:151], v[132:135], v[0:15]
	s_lshr_b32 s4, s35, 6
	s_mulk_i32 s4, 0xc00
	s_ashr_i32 s5, s4, 31
	s_lshl_b64 s[4:5], s[4:5], 2
	s_add_u32 s4, s49, s4
	s_addc_u32 s5, s50, s5
	s_add_i32 s10, s10, s51
	v_or_b32_e32 v128, s10, v201
	v_ashrrev_i32_e32 v129, 31, v128
	v_lshlrev_b64 v[162:163], 12, v[128:129]
	v_or_b32_e32 v128, s10, v202
	v_ashrrev_i32_e32 v129, 31, v128
	v_lshlrev_b64 v[174:175], 12, v[128:129]
	v_or_b32_e32 v128, s10, v203
	v_ashrrev_i32_e32 v129, 31, v128
	v_lshlrev_b64 v[188:189], 12, v[128:129]
	v_or_b32_e32 v128, s10, v204
	v_or_b32_e32 v134, s10, v207
	v_ashrrev_i32_e32 v129, 31, v128
	v_ashrrev_i32_e32 v135, 31, v134
	v_lshlrev_b64 v[150:151], 12, v[128:129]
	v_or_b32_e32 v128, s10, v205
	v_or_b32_e32 v130, s10, v206
	v_lshlrev_b64 v[140:141], 12, v[134:135]
	v_or_b32_e32 v134, s10, v208
	s_waitcnt vmcnt(0) lgkmcnt(0)
	s_barrier
	v_ashrrev_i32_e32 v129, 31, v128
	v_ashrrev_i32_e32 v131, 31, v130
	v_ashrrev_i32_e32 v135, 31, v134
	ds_write_b128 v211, v[112:115]
	ds_write_b128 v211, v[116:119] offset:32
	ds_write_b128 v211, v[120:123] offset:64
	ds_write_b128 v211, v[124:127] offset:96
	ds_write_b128 v211, v[96:99] offset:128
	ds_write_b128 v211, v[100:103] offset:160
	ds_write_b128 v211, v[104:107] offset:192
	ds_write_b128 v211, v[108:111] offset:224
	v_or_b32_e32 v100, s8, v192
	v_lshl_add_u64 v[132:133], s[8:9], 2, v[178:179]
	v_lshlrev_b64 v[148:149], 12, v[128:129]
	v_lshlrev_b64 v[142:143], 12, v[130:131]
	v_lshlrev_b64 v[134:135], 12, v[134:135]
	s_add_u32 s4, s4, 0x26c2000
	v_ashrrev_i32_e32 v101, 31, v100
	v_lshl_add_u64 v[152:153], v[132:133], 0, v[174:175]
	v_lshl_add_u64 v[144:145], v[132:133], 0, v[188:189]
	v_lshl_add_u64 v[136:137], v[132:133], 0, v[150:151]
	v_lshl_add_u64 v[128:129], v[132:133], 0, v[148:149]
	v_lshl_add_u64 v[130:131], v[132:133], 0, v[142:143]
	v_lshl_add_u64 v[138:139], v[132:133], 0, v[140:141]
	v_lshl_add_u64 v[146:147], v[132:133], 0, v[134:135]
	s_addc_u32 s5, s5, 0
	v_lshlrev_b64 v[102:103], 2, v[100:101]
	v_lshl_add_u64 v[164:165], v[132:133], 0, v[162:163]
	v_lshl_add_u64 v[160:161], s[4:5], 0, v[102:103]
	global_load_dwordx4 v[96:99], v[146:147], off offset:256
	global_load_dwordx4 v[108:111], v[146:147], off
	global_load_dwordx4 v[104:107], v[138:139], off offset:256
	global_load_dwordx4 v[116:119], v[138:139], off
	global_load_dwordx4 v[112:115], v[130:131], off offset:256
	global_load_dwordx4 v[124:127], v[130:131], off
	global_load_dwordx4 v[120:123], v[128:129], off offset:256
	global_load_dwordx4 v[156:159], v[128:129], off
	s_nop 0
	global_load_dwordx4 v[128:131], v[136:137], off offset:256
	global_load_dwordx4 v[166:169], v[136:137], off
	s_nop 0
	global_load_dwordx4 v[136:139], v[144:145], off offset:256
	global_load_dwordx4 v[170:173], v[144:145], off
	s_nop 0
	global_load_dwordx4 v[144:147], v[152:153], off offset:256
	global_load_dwordx4 v[184:187], v[152:153], off
	s_nop 0
	global_load_dwordx4 v[152:155], v[164:165], off offset:256
	global_load_dwordx4 v[214:217], v[164:165], off
	s_waitcnt lgkmcnt(0)
	global_load_dwordx4 v[218:221], v[160:161], off
	v_lshlrev_b32_e32 v246, 4, v199
	v_add_u32_e32 v246, 0x22080, v246
	ds_read_b128 v[222:225], v212
	ds_read_b128 v[226:229], v212 offset:1088
	v_lshl_add_u64 v[164:165], s[28:29], 0, v[102:103]
	v_lshl_add_u64 v[230:231], v[164:165], 0, v[162:163]
	s_or_b32 s8, s10, 32
	v_or_b32_e32 v100, 64, v100
	v_or_b32_e32 v102, s8, v201
	v_ashrrev_i32_e32 v101, 31, v100
	v_ashrrev_i32_e32 v103, 31, v102
	v_lshl_add_u64 v[162:163], v[100:101], 2, s[4:5]
	v_readlane_b32 s4, v255, 10
	s_add_i32 s66, s66, s4
	s_and_b64 vcc, exec, s[6:7]
	s_waitcnt vmcnt(0) lgkmcnt(1)
	ds_write_b128 v246, v[218:221]
	v_pk_fma_f32 v[214:215], v[222:223], v[218:219], v[214:215]
	v_pk_fma_f32 v[216:217], v[224:225], v[220:221], v[216:217]
	global_store_dwordx4 v[230:231], v[214:217], off nt
	s_nop 0
	ds_read_b128 v[214:217], v246
	v_lshl_add_u64 v[222:223], v[164:165], 0, v[174:175]
	v_lshl_add_u64 v[224:225], v[164:165], 0, v[188:189]
	v_lshlrev_b64 v[188:189], 12, v[102:103]
	ds_read_b128 v[218:221], v212 offset:3264
	s_waitcnt lgkmcnt(1)
; #define WSYNC() asm volatile("s_waitcnt lgkmcnt(0)" ::: "memory")
; #define LOADX(ps_) do { _Pragma("unroll") for (int it = 0; it < 8; ++it) { const int id = it * 64 + lane, row = id >> 4, c = id & 15; \
;           xn[it] = *(const float4*)(xin + (size_t)(m0 + wm * 64 + ((ps_) >> 1) * 32 + row) * 1024 + n0 + wn * 128 + ((ps_) & 1) * 64 + c * 4); } } while (0)
; template <int EPI>
; DI void gemm_phase(const Params& p, char* lds, const bfu* __restrict__ A, const bfu* __restrict__ BT, int ntn, int l, const float* xin) {
;     ...
;       for (int ps = 0; ps < 4; ++ps) {
;         const int i = ps >> 1, jp = ps & 1;
;         float4 xc[8];
; #pragma unroll
;         for (int it = 0; it < 8; ++it) xc[it] = xn[it];
;         if (ps + 1 < 4) LOADX(ps + 1);
;         if (ps) WSYNC();
; #pragma unroll
;         for (int j2 = 0; j2 < 2; ++j2)
; #pragma unroll
;           for (int g = 0; g < 4; ++g) {
;             const f32x16& a = acc[i][2 * jp + j2];
;             float4 o; o.x = a[4 * g]; o.y = a[4 * g + 1]; o.z = a[4 * g + 2]; o.w = a[4 * g + 3];
;             *(float4*)(stg + r * 272 + (j2 * 32 + 8 * g + 4 * h) * 4) = o;
;           }
;         WSYNC();
; #pragma unroll
;         for (int it = 0; it < 8; ++it) {
;           const int id = it * 64 + lane, row = id >> 4, c = id & 15;
;           const float4 y = *(const float4*)(stg + row * 272 + c * 16);
;           const int m = m0 + wm * 64 + i * 32 + row, n = n0 + wn * 128 + jp * 64 + c * 4;
;           const float4 xv = xc[it];
;           const float4 gv = *(const float4*)(gate + n);
;           float4 o; o.x = xv.x + gv.x * y.x; o.y = xv.y + gv.y * y.y; o.z = xv.z + gv.z * y.z; o.w = xv.w + gv.w * y.w;
;           *(float4*)(p.out + (size_t)m * 1024 + n) = o;
;         }
	v_pk_fma_f32 v[184:185], v[226:227], v[214:215], v[184:185]
	v_pk_fma_f32 v[186:187], v[228:229], v[216:217], v[186:187]
	global_store_dwordx4 v[222:223], v[184:187], off nt
	s_nop 0
	ds_read_b128 v[184:187], v246
	ds_read_b128 v[214:217], v212 offset:2176
	v_lshl_add_u64 v[226:227], v[164:165], 0, v[134:135]
	v_lshl_add_u64 v[228:229], v[132:133], 0, v[188:189]
	s_waitcnt lgkmcnt(0)
	v_pk_fma_f32 v[170:171], v[214:215], v[184:185], v[170:171]
	v_pk_fma_f32 v[172:173], v[216:217], v[186:187], v[172:173]
	global_store_dwordx4 v[224:225], v[170:173], off nt
	s_nop 0
	ds_read_b128 v[170:173], v246
	v_lshl_add_u64 v[214:215], v[164:165], 0, v[150:151]
	v_lshl_add_u64 v[216:217], v[164:165], 0, v[148:149]
	ds_read_b128 v[148:151], v212 offset:5440
	s_waitcnt lgkmcnt(1)
	v_pk_fma_f32 v[166:167], v[218:219], v[170:171], v[166:167]
	v_pk_fma_f32 v[168:169], v[220:221], v[172:173], v[168:169]
	global_store_dwordx4 v[214:215], v[166:169], off nt
	s_nop 0
	ds_read_b128 v[166:169], v246
	ds_read_b128 v[170:173], v212 offset:4352
	v_lshl_add_u64 v[218:219], v[164:165], 0, v[142:143]
	v_lshl_add_u64 v[220:221], v[164:165], 0, v[140:141]
	ds_read_b128 v[140:143], v212 offset:7616
	s_waitcnt lgkmcnt(1)
	v_pk_fma_f32 v[156:157], v[170:171], v[166:167], v[156:157]
	v_pk_fma_f32 v[158:159], v[172:173], v[168:169], v[158:159]
	global_store_dwordx4 v[216:217], v[156:159], off nt
	s_nop 0
	ds_read_b128 v[156:159], v246
	v_or_b32_e32 v166, s8, v208
	v_ashrrev_i32_e32 v167, 31, v166
	v_lshlrev_b64 v[166:167], 12, v[166:167]
	v_lshl_add_u64 v[236:237], v[132:133], 0, v[166:167]
	s_waitcnt lgkmcnt(0)
	v_pk_fma_f32 v[124:125], v[148:149], v[156:157], v[124:125]
	v_pk_fma_f32 v[126:127], v[150:151], v[158:159], v[126:127]
	global_store_dwordx4 v[218:219], v[124:127], off nt
	s_nop 0
	ds_read_b128 v[124:127], v246
	ds_read_b128 v[148:151], v212 offset:6528
	v_or_b32_e32 v156, s8, v206
	v_or_b32_e32 v158, s8, v207
	v_ashrrev_i32_e32 v157, 31, v156
	v_ashrrev_i32_e32 v159, 31, v158
	v_lshlrev_b64 v[170:171], 12, v[156:157]
	v_lshlrev_b64 v[168:169], 12, v[158:159]
	v_lshl_add_u64 v[250:251], v[132:133], 0, v[170:171]
	v_lshl_add_u64 v[252:253], v[132:133], 0, v[168:169]
	s_waitcnt lgkmcnt(0)
	v_pk_fma_f32 v[116:117], v[148:149], v[124:125], v[116:117]
	v_pk_fma_f32 v[118:119], v[150:151], v[126:127], v[118:119]
	global_store_dwordx4 v[220:221], v[116:119], off nt
	s_nop 0
	ds_read_b128 v[116:119], v246
	v_or_b32_e32 v124, s8, v202
	v_or_b32_e32 v126, s8, v203
	v_or_b32_e32 v148, s8, v204
	v_or_b32_e32 v150, s8, v205
	v_ashrrev_i32_e32 v125, 31, v124
	v_ashrrev_i32_e32 v127, 31, v126
	v_ashrrev_i32_e32 v149, 31, v148
	v_ashrrev_i32_e32 v151, 31, v150
	v_lshlrev_b64 v[186:187], 12, v[124:125]
	v_lshlrev_b64 v[184:185], 12, v[126:127]
	v_lshlrev_b64 v[174:175], 12, v[148:149]
	v_lshlrev_b64 v[172:173], 12, v[150:151]
	v_lshl_add_u64 v[232:233], v[132:133], 0, v[186:187]
	v_lshl_add_u64 v[240:241], v[132:133], 0, v[184:185]
	v_lshl_add_u64 v[242:243], v[132:133], 0, v[174:175]
	v_lshl_add_u64 v[248:249], v[132:133], 0, v[172:173]
	s_waitcnt lgkmcnt(0)
	v_pk_fma_f32 v[100:101], v[140:141], v[116:117], v[108:109]
	v_pk_fma_f32 v[102:103], v[142:143], v[118:119], v[110:111]
	global_store_dwordx4 v[226:227], v[100:103], off nt
	global_load_dwordx4 v[100:103], v[236:237], off
	s_nop 0
	global_load_dwordx4 v[108:111], v[252:253], off
	global_load_dwordx4 v[116:119], v[250:251], off
	global_load_dwordx4 v[124:127], v[248:249], off
	global_load_dwordx4 v[132:135], v[242:243], off
	global_load_dwordx4 v[140:143], v[240:241], off
	global_load_dwordx4 v[148:151], v[232:233], off
	global_load_dwordx4 v[156:159], v[228:229], off
	s_waitcnt lgkmcnt(0)
	ds_write_b128 v211, v[80:83]
	ds_write_b128 v211, v[84:87] offset:32
	ds_write_b128 v211, v[88:91] offset:64
	ds_write_b128 v211, v[92:95] offset:96
	ds_write_b128 v211, v[64:67] offset:128
	ds_write_b128 v211, v[68:71] offset:160
	ds_write_b128 v211, v[72:75] offset:192
	ds_write_b128 v211, v[76:79] offset:224
	s_waitcnt lgkmcnt(0)
	global_load_dwordx4 v[64:67], v[162:163], off
	ds_read_b128 v[68:71], v212
	ds_read_b128 v[72:75], v212 offset:1088
	s_waitcnt vmcnt(0) lgkmcnt(1)
	ds_write_b128 v246, v[64:67] offset:8192
	v_pk_fma_f32 v[64:65], v[68:69], v[64:65], v[152:153]
	v_pk_fma_f32 v[66:67], v[70:71], v[66:67], v[154:155]
	global_store_dwordx4 v[230:231], v[64:67], off offset:256 nt
	s_nop 0
	ds_read_b128 v[64:67], v246 offset:8192
	s_waitcnt lgkmcnt(0)
	v_pk_fma_f32 v[64:65], v[72:73], v[64:65], v[144:145]
	v_pk_fma_f32 v[66:67], v[74:75], v[66:67], v[146:147]
	global_store_dwordx4 v[222:223], v[64:67], off offset:256 nt
	s_nop 0
	ds_read_b128 v[64:67], v246 offset:8192
	ds_read_b128 v[68:71], v212 offset:2176
	ds_read_b128 v[72:75], v212 offset:3264
	s_waitcnt lgkmcnt(1)
	v_pk_fma_f32 v[64:65], v[68:69], v[64:65], v[136:137]
	v_pk_fma_f32 v[66:67], v[70:71], v[66:67], v[138:139]
	global_store_dwordx4 v[224:225], v[64:67], off offset:256 nt
	s_nop 0
	ds_read_b128 v[64:67], v246 offset:8192
	s_waitcnt lgkmcnt(0)
	v_pk_fma_f32 v[64:65], v[72:73], v[64:65], v[128:129]
	v_pk_fma_f32 v[66:67], v[74:75], v[66:67], v[130:131]
	global_store_dwordx4 v[214:215], v[64:67], off offset:256 nt
	s_nop 0
	ds_read_b128 v[64:67], v246 offset:8192
	ds_read_b128 v[68:71], v212 offset:4352
	ds_read_b128 v[72:75], v212 offset:5440
	s_waitcnt lgkmcnt(1)
	v_pk_fma_f32 v[64:65], v[68:69], v[64:65], v[120:121]
	v_pk_fma_f32 v[66:67], v[70:71], v[66:67], v[122:123]
	global_store_dwordx4 v[216:217], v[64:67], off offset:256 nt
	s_nop 0
	ds_read_b128 v[64:67], v246 offset:8192
	s_waitcnt lgkmcnt(0)
; #define WSYNC() asm volatile("s_waitcnt lgkmcnt(0)" ::: "memory")
; #define LOADX(ps_) do { _Pragma("unroll") for (int it = 0; it < 8; ++it) { const int id = it * 64 + lane, row = id >> 4, c = id & 15; \
;           xn[it] = *(const float4*)(xin + (size_t)(m0 + wm * 64 + ((ps_) >> 1) * 32 + row) * 1024 + n0 + wn * 128 + ((ps_) & 1) * 64 + c * 4); } } while (0)
; template <int EPI>
; DI void gemm_phase(const Params& p, char* lds, const bfu* __restrict__ A, const bfu* __restrict__ BT, int ntn, int l, const float* xin) {
;     ...
;       for (int ps = 0; ps < 4; ++ps) {
;         const int i = ps >> 1, jp = ps & 1;
;         float4 xc[8];
; #pragma unroll
;         for (int it = 0; it < 8; ++it) xc[it] = xn[it];
;         if (ps + 1 < 4) LOADX(ps + 1);
;         if (ps) WSYNC();
; #pragma unroll
;         for (int j2 = 0; j2 < 2; ++j2)
; #pragma unroll
;           for (int g = 0; g < 4; ++g) {
;             const f32x16& a = acc[i][2 * jp + j2];
;             float4 o; o.x = a[4 * g]; o.y = a[4 * g + 1]; o.z = a[4 * g + 2]; o.w = a[4 * g + 3];
;             *(float4*)(stg + r * 272 + (j2 * 32 + 8 * g + 4 * h) * 4) = o;
;           }
;         WSYNC();
; #pragma unroll
;         for (int it = 0; it < 8; ++it) {
;           const int id = it * 64 + lane, row = id >> 4, c = id & 15;
;           const float4 y = *(const float4*)(stg + row * 272 + c * 16);
;           const int m = m0 + wm * 64 + i * 32 + row, n = n0 + wn * 128 + jp * 64 + c * 4;
;           const float4 xv = xc[it];
;           const float4 gv = *(const float4*)(gate + n);
;           float4 o; o.x = xv.x + gv.x * y.x; o.y = xv.y + gv.y * y.y; o.z = xv.z + gv.z * y.z; o.w = xv.w + gv.w * y.w;
;           *(float4*)(p.out + (size_t)m * 1024 + n) = o;
;         }
	v_pk_fma_f32 v[64:65], v[72:73], v[64:65], v[112:113]
	v_pk_fma_f32 v[66:67], v[74:75], v[66:67], v[114:115]
	global_store_dwordx4 v[218:219], v[64:67], off offset:256 nt
	s_nop 0
	ds_read_b128 v[64:67], v246 offset:8192
	ds_read_b128 v[68:71], v212 offset:6528
	ds_read_b128 v[72:75], v212 offset:7616
	s_waitcnt lgkmcnt(1)
	v_pk_fma_f32 v[64:65], v[68:69], v[64:65], v[104:105]
	v_pk_fma_f32 v[66:67], v[70:71], v[66:67], v[106:107]
	global_store_dwordx4 v[220:221], v[64:67], off offset:256 nt
	s_nop 0
	ds_read_b128 v[64:67], v246 offset:8192
	s_waitcnt lgkmcnt(0)
	v_pk_fma_f32 v[64:65], v[72:73], v[64:65], v[96:97]
	v_pk_fma_f32 v[66:67], v[74:75], v[66:67], v[98:99]
	global_store_dwordx4 v[226:227], v[64:67], off offset:256 nt
	global_load_dwordx4 v[64:67], v[236:237], off offset:256
	s_nop 0
	global_load_dwordx4 v[68:71], v[252:253], off offset:256
	global_load_dwordx4 v[72:75], v[250:251], off offset:256
	global_load_dwordx4 v[76:79], v[248:249], off offset:256
	global_load_dwordx4 v[80:83], v[242:243], off offset:256
	global_load_dwordx4 v[84:87], v[240:241], off offset:256
	global_load_dwordx4 v[88:91], v[232:233], off offset:256
	global_load_dwordx4 v[92:95], v[228:229], off offset:256
	s_waitcnt lgkmcnt(0)
	ds_write_b128 v211, v[48:51]
	ds_write_b128 v211, v[52:55] offset:32
	ds_write_b128 v211, v[56:59] offset:64
	ds_write_b128 v211, v[60:63] offset:96
	ds_write_b128 v211, v[32:35] offset:128
	ds_write_b128 v211, v[36:39] offset:160
	ds_write_b128 v211, v[40:43] offset:192
	ds_write_b128 v211, v[44:47] offset:224
	s_waitcnt lgkmcnt(0)
	s_nop 0
	ds_read_b128 v[32:35], v246
	ds_read_b128 v[36:39], v212
	ds_read_b128 v[40:43], v212 offset:1088
	v_lshl_add_u64 v[44:45], v[164:165], 0, v[188:189]
	v_lshl_add_u64 v[46:47], v[164:165], 0, v[186:187]
	v_lshl_add_u64 v[48:49], v[164:165], 0, v[184:185]
	v_lshl_add_u64 v[50:51], v[164:165], 0, v[174:175]
	v_lshl_add_u64 v[52:53], v[164:165], 0, v[172:173]
	v_lshl_add_u64 v[54:55], v[164:165], 0, v[170:171]
	v_lshl_add_u64 v[56:57], v[164:165], 0, v[168:169]
	s_waitcnt vmcnt(0) lgkmcnt(1)
	v_pk_fma_f32 v[32:33], v[36:37], v[32:33], v[156:157]
	v_pk_fma_f32 v[34:35], v[38:39], v[34:35], v[158:159]
	global_store_dwordx4 v[44:45], v[32:35], off nt
	s_nop 0
	ds_read_b128 v[32:35], v246
	ds_read_b128 v[36:39], v212 offset:2176
	s_waitcnt lgkmcnt(1)
	v_pk_fma_f32 v[32:33], v[40:41], v[32:33], v[148:149]
	v_pk_fma_f32 v[34:35], v[42:43], v[34:35], v[150:151]
	global_store_dwordx4 v[46:47], v[32:35], off nt
	s_nop 0
	ds_read_b128 v[32:35], v246
	ds_read_b128 v[40:43], v212 offset:3264
	s_waitcnt lgkmcnt(1)
	v_pk_fma_f32 v[32:33], v[36:37], v[32:33], v[140:141]
	v_pk_fma_f32 v[34:35], v[38:39], v[34:35], v[142:143]
	global_store_dwordx4 v[48:49], v[32:35], off nt
	s_nop 0
	ds_read_b128 v[32:35], v246
	ds_read_b128 v[36:39], v212 offset:4352
	s_waitcnt lgkmcnt(1)
	v_pk_fma_f32 v[32:33], v[40:41], v[32:33], v[132:133]
	v_pk_fma_f32 v[34:35], v[42:43], v[34:35], v[134:135]
	global_store_dwordx4 v[50:51], v[32:35], off nt
	s_nop 0
	ds_read_b128 v[32:35], v246
	ds_read_b128 v[40:43], v212 offset:5440
	s_waitcnt lgkmcnt(1)
	v_pk_fma_f32 v[32:33], v[36:37], v[32:33], v[124:125]
	v_pk_fma_f32 v[34:35], v[38:39], v[34:35], v[126:127]
	global_store_dwordx4 v[52:53], v[32:35], off nt
	s_nop 0
	ds_read_b128 v[32:35], v246
	ds_read_b128 v[36:39], v212 offset:6528
	s_waitcnt lgkmcnt(1)
	v_pk_fma_f32 v[32:33], v[40:41], v[32:33], v[116:117]
	v_pk_fma_f32 v[34:35], v[42:43], v[34:35], v[118:119]
	global_store_dwordx4 v[54:55], v[32:35], off nt
	s_nop 0
	ds_read_b128 v[32:35], v246
	ds_read_b128 v[40:43], v212 offset:7616
	s_waitcnt lgkmcnt(1)
	v_pk_fma_f32 v[32:33], v[36:37], v[32:33], v[108:109]
	v_pk_fma_f32 v[34:35], v[38:39], v[34:35], v[110:111]
	global_store_dwordx4 v[56:57], v[32:35], off nt
	s_nop 0
	ds_read_b128 v[32:35], v246
	v_lshl_add_u64 v[36:37], v[164:165], 0, v[166:167]
	s_waitcnt lgkmcnt(0)
	v_pk_fma_f32 v[32:33], v[40:41], v[32:33], v[100:101]
	v_pk_fma_f32 v[34:35], v[42:43], v[34:35], v[102:103]
	global_store_dwordx4 v[36:37], v[32:35], off nt
	s_waitcnt lgkmcnt(0)
	ds_write_b128 v211, v[16:19]
	ds_write_b128 v211, v[20:23] offset:32
	ds_write_b128 v211, v[24:27] offset:64
	ds_write_b128 v211, v[28:31] offset:96
	ds_write_b128 v211, v[0:3] offset:128
	ds_write_b128 v211, v[4:7] offset:160
	ds_write_b128 v211, v[8:11] offset:192
	ds_write_b128 v211, v[12:15] offset:224
	s_waitcnt lgkmcnt(0)
	s_nop 0
	ds_read_b128 v[0:3], v246 offset:8192
	ds_read_b128 v[4:7], v212
	ds_read_b128 v[8:11], v212 offset:1088
	s_waitcnt vmcnt(0) lgkmcnt(1)
	v_pk_fma_f32 v[0:1], v[4:5], v[0:1], v[92:93]
	v_pk_fma_f32 v[2:3], v[6:7], v[2:3], v[94:95]
	global_store_dwordx4 v[44:45], v[0:3], off offset:256 nt
	s_nop 0
	ds_read_b128 v[0:3], v246 offset:8192
	s_waitcnt lgkmcnt(0)
	v_pk_fma_f32 v[0:1], v[8:9], v[0:1], v[88:89]
	v_pk_fma_f32 v[2:3], v[10:11], v[2:3], v[90:91]
	global_store_dwordx4 v[46:47], v[0:3], off offset:256 nt
	s_nop 0
	ds_read_b128 v[0:3], v246 offset:8192
	ds_read_b128 v[4:7], v212 offset:2176
	ds_read_b128 v[8:11], v212 offset:3264
	s_waitcnt lgkmcnt(1)
	v_pk_fma_f32 v[0:1], v[4:5], v[0:1], v[84:85]
	v_pk_fma_f32 v[2:3], v[6:7], v[2:3], v[86:87]
	global_store_dwordx4 v[48:49], v[0:3], off offset:256 nt
	s_nop 0
	ds_read_b128 v[0:3], v246 offset:8192
	s_waitcnt lgkmcnt(0)
	v_pk_fma_f32 v[0:1], v[8:9], v[0:1], v[80:81]
	v_pk_fma_f32 v[2:3], v[10:11], v[2:3], v[82:83]
	global_store_dwordx4 v[50:51], v[0:3], off offset:256 nt
	s_nop 0
	ds_read_b128 v[0:3], v246 offset:8192
	ds_read_b128 v[4:7], v212 offset:4352
	ds_read_b128 v[8:11], v212 offset:5440
	s_waitcnt lgkmcnt(1)
	v_pk_fma_f32 v[0:1], v[4:5], v[0:1], v[76:77]
	v_pk_fma_f32 v[2:3], v[6:7], v[2:3], v[78:79]
	global_store_dwordx4 v[52:53], v[0:3], off offset:256 nt
	s_nop 0
	ds_read_b128 v[0:3], v246 offset:8192
	s_waitcnt lgkmcnt(0)
	v_pk_fma_f32 v[0:1], v[8:9], v[0:1], v[72:73]
	v_pk_fma_f32 v[2:3], v[10:11], v[2:3], v[74:75]
	global_store_dwordx4 v[54:55], v[0:3], off offset:256 nt
	s_nop 0
	ds_read_b128 v[0:3], v246 offset:8192
	ds_read_b128 v[4:7], v212 offset:6528
	ds_read_b128 v[8:11], v212 offset:7616
	s_waitcnt lgkmcnt(1)
	v_pk_fma_f32 v[0:1], v[4:5], v[0:1], v[68:69]
	v_pk_fma_f32 v[2:3], v[6:7], v[2:3], v[70:71]
	global_store_dwordx4 v[56:57], v[0:3], off offset:256 nt
	s_nop 0
	ds_read_b128 v[0:3], v246 offset:8192
	s_waitcnt lgkmcnt(0)
	v_pk_fma_f32 v[0:1], v[8:9], v[0:1], v[64:65]
	v_pk_fma_f32 v[2:3], v[10:11], v[2:3], v[66:67]
	global_store_dwordx4 v[36:37], v[0:3], off offset:256 nt
	s_cbranch_vccnz .LBB0_822
